# attn_combine: 8 loop iterations batched, all 48 loads issued before the first wait (counted vmcnt), global_load with SGPR base
# baseline (speedup 1.0000x reference)
.LBB0_328:
	s_waitcnt vmcnt(0) lgkmcnt(0)
	s_lshl_b32 s0, s23, 3
	s_add_i32 s0, s0, s20
	s_cmpk_gt_i32 s0, 0x7fff
	s_barrier
	s_cbranch_scc1 .LBB0_331
	s_lshl_b32 s1, s21, 3
	s_add_u32 s4, s12, 0x37e00000
	s_addc_u32 s5, s13, 0
	s_add_u32 s2, s12, 0x3de00000
	s_addc_u32 s3, s13, 0
	s_add_u32 s6, s12, 0x38e00000
	s_addc_u32 s7, s13, 0
	s_add_u32 s12, s12, 0x39e00000
	s_addc_u32 s13, s13, 0
	s_and_b32 s14, s20, 7
	s_lshl_b32 s56, s14, 7
	s_lshl_b32 s15, s14, 8
	v_lshlrev_b32_e32 v2, 1, v128
	s_add_u32 s10, s10, s15
	v_ashrrev_i32_e32 v3, 31, v2
	v_ashrrev_i32_e32 v129, 31, v128
	s_addc_u32 s11, s11, 0
	v_lshl_add_u64 v[2:3], v[2:3], 0, s[56:57]
	v_lshl_add_u64 v[4:5], v[128:129], 2, s[10:11]
	s_lshl_b32 s14, s14, 2
	v_lshlrev_b32_e32 v15, 1, v2
.Lcmb_blk:
	s_mul_i32 s16, s1, 7
	s_add_i32 s16, s16, s0
	s_cmp_lt_i32 s16, 0x8000
	s_cbranch_scc0 .LBB0_330
	s_ashr_i32 s10, s0, 3
	s_add_i32 s10, s10, s22
	s_ashr_i32 s11, s10, 31
	s_lshl_b64 s[16:17], s[10:11], 5
	s_add_u32 s16, s2, s16
	s_addc_u32 s17, s3, s17
	s_add_u32 s16, s16, s14
	s_addc_u32 s17, s17, 0
	global_load_dword v16, v1, s[16:17]
	s_add_u32 s16, s16, 0x40000
	s_addc_u32 s17, s17, 0
	global_load_dword v17, v1, s[16:17]
	s_add_u32 s16, s16, 0x40000
	s_addc_u32 s17, s17, 0
	global_load_dword v18, v1, s[16:17]
	s_lshl_b64 s[16:17], s[10:11], 11
	s_add_u32 s16, s4, s16
	s_addc_u32 s17, s5, s17
	global_load_dword v19, v15, s[16:17]
	s_lshl_b64 s[16:17], s[10:11], 11
	s_add_u32 s16, s6, s16
	s_addc_u32 s17, s7, s17
	global_load_dword v20, v15, s[16:17]
	s_lshl_b64 s[16:17], s[10:11], 11
	s_add_u32 s16, s12, s16
	s_addc_u32 s17, s13, s17
	global_load_dword v21, v15, s[16:17]
	s_lshl_b64 s[16:17], s[10:11], 12
	v_lshl_add_u64 v[22:23], v[4:5], 0, s[16:17]
	s_add_i32 s0, s0, s1
	s_ashr_i32 s10, s0, 3
	s_add_i32 s10, s10, s22
	s_ashr_i32 s11, s10, 31
	s_lshl_b64 s[16:17], s[10:11], 5
	s_add_u32 s16, s2, s16
	s_addc_u32 s17, s3, s17
	s_add_u32 s16, s16, s14
	s_addc_u32 s17, s17, 0
	global_load_dword v24, v1, s[16:17]
	s_add_u32 s16, s16, 0x40000
	s_addc_u32 s17, s17, 0
	global_load_dword v25, v1, s[16:17]
	s_add_u32 s16, s16, 0x40000
	s_addc_u32 s17, s17, 0
	global_load_dword v26, v1, s[16:17]
	s_lshl_b64 s[16:17], s[10:11], 11
	s_add_u32 s16, s4, s16
	s_addc_u32 s17, s5, s17
	global_load_dword v27, v15, s[16:17]
	s_lshl_b64 s[16:17], s[10:11], 11
	s_add_u32 s16, s6, s16
	s_addc_u32 s17, s7, s17
	global_load_dword v28, v15, s[16:17]
	s_lshl_b64 s[16:17], s[10:11], 11
	s_add_u32 s16, s12, s16
	s_addc_u32 s17, s13, s17
	global_load_dword v29, v15, s[16:17]
	s_lshl_b64 s[16:17], s[10:11], 12
	v_lshl_add_u64 v[30:31], v[4:5], 0, s[16:17]
	s_add_i32 s0, s0, s1
	s_ashr_i32 s10, s0, 3
	s_add_i32 s10, s10, s22
	s_ashr_i32 s11, s10, 31
	s_lshl_b64 s[16:17], s[10:11], 5
	s_add_u32 s16, s2, s16
	s_addc_u32 s17, s3, s17
	s_add_u32 s16, s16, s14
	s_addc_u32 s17, s17, 0
	global_load_dword v32, v1, s[16:17]
	s_add_u32 s16, s16, 0x40000
	s_addc_u32 s17, s17, 0
	global_load_dword v33, v1, s[16:17]
	s_add_u32 s16, s16, 0x40000
	s_addc_u32 s17, s17, 0
	global_load_dword v34, v1, s[16:17]
	s_lshl_b64 s[16:17], s[10:11], 11
	s_add_u32 s16, s4, s16
	s_addc_u32 s17, s5, s17
	global_load_dword v35, v15, s[16:17]
	s_lshl_b64 s[16:17], s[10:11], 11
	s_add_u32 s16, s6, s16
	s_addc_u32 s17, s7, s17
	global_load_dword v36, v15, s[16:17]
	s_lshl_b64 s[16:17], s[10:11], 11
	s_add_u32 s16, s12, s16
	s_addc_u32 s17, s13, s17
	global_load_dword v37, v15, s[16:17]
	s_lshl_b64 s[16:17], s[10:11], 12
	v_lshl_add_u64 v[38:39], v[4:5], 0, s[16:17]
	s_add_i32 s0, s0, s1
	s_ashr_i32 s10, s0, 3
	s_add_i32 s10, s10, s22
	s_ashr_i32 s11, s10, 31
	s_lshl_b64 s[16:17], s[10:11], 5
	s_add_u32 s16, s2, s16
	s_addc_u32 s17, s3, s17
	s_add_u32 s16, s16, s14
	s_addc_u32 s17, s17, 0
	global_load_dword v40, v1, s[16:17]
	s_add_u32 s16, s16, 0x40000
	s_addc_u32 s17, s17, 0
	global_load_dword v41, v1, s[16:17]
	s_add_u32 s16, s16, 0x40000
	s_addc_u32 s17, s17, 0
	global_load_dword v42, v1, s[16:17]
	s_lshl_b64 s[16:17], s[10:11], 11
	s_add_u32 s16, s4, s16
	s_addc_u32 s17, s5, s17
	global_load_dword v43, v15, s[16:17]
	s_lshl_b64 s[16:17], s[10:11], 11
	s_add_u32 s16, s6, s16
	s_addc_u32 s17, s7, s17
	global_load_dword v44, v15, s[16:17]
	s_lshl_b64 s[16:17], s[10:11], 11
	s_add_u32 s16, s12, s16
	s_addc_u32 s17, s13, s17
	global_load_dword v45, v15, s[16:17]
	s_lshl_b64 s[16:17], s[10:11], 12
	v_lshl_add_u64 v[46:47], v[4:5], 0, s[16:17]
	s_add_i32 s0, s0, s1
	s_ashr_i32 s10, s0, 3
	s_add_i32 s10, s10, s22
	s_ashr_i32 s11, s10, 31
	s_lshl_b64 s[16:17], s[10:11], 5
	s_add_u32 s16, s2, s16
	s_addc_u32 s17, s3, s17
	s_add_u32 s16, s16, s14
	s_addc_u32 s17, s17, 0
	global_load_dword v48, v1, s[16:17]
	s_add_u32 s16, s16, 0x40000
	s_addc_u32 s17, s17, 0
	global_load_dword v49, v1, s[16:17]
	s_add_u32 s16, s16, 0x40000
	s_addc_u32 s17, s17, 0
	global_load_dword v50, v1, s[16:17]
	s_lshl_b64 s[16:17], s[10:11], 11
	s_add_u32 s16, s4, s16
	s_addc_u32 s17, s5, s17
	global_load_dword v51, v15, s[16:17]
	s_lshl_b64 s[16:17], s[10:11], 11
	s_add_u32 s16, s6, s16
	s_addc_u32 s17, s7, s17
	global_load_dword v52, v15, s[16:17]
	s_lshl_b64 s[16:17], s[10:11], 11
	s_add_u32 s16, s12, s16
	s_addc_u32 s17, s13, s17
	global_load_dword v53, v15, s[16:17]
	s_lshl_b64 s[16:17], s[10:11], 12
	v_lshl_add_u64 v[54:55], v[4:5], 0, s[16:17]
	s_add_i32 s0, s0, s1
	s_ashr_i32 s10, s0, 3
	s_add_i32 s10, s10, s22
	s_ashr_i32 s11, s10, 31
	s_lshl_b64 s[16:17], s[10:11], 5
	s_add_u32 s16, s2, s16
	s_addc_u32 s17, s3, s17
	s_add_u32 s16, s16, s14
	s_addc_u32 s17, s17, 0
	global_load_dword v56, v1, s[16:17]
	s_add_u32 s16, s16, 0x40000
	s_addc_u32 s17, s17, 0
	global_load_dword v57, v1, s[16:17]
	s_add_u32 s16, s16, 0x40000
	s_addc_u32 s17, s17, 0
	global_load_dword v58, v1, s[16:17]
	s_lshl_b64 s[16:17], s[10:11], 11
	s_add_u32 s16, s4, s16
	s_addc_u32 s17, s5, s17
	global_load_dword v59, v15, s[16:17]
	s_lshl_b64 s[16:17], s[10:11], 11
	s_add_u32 s16, s6, s16
	s_addc_u32 s17, s7, s17
	global_load_dword v60, v15, s[16:17]
	s_lshl_b64 s[16:17], s[10:11], 11
	s_add_u32 s16, s12, s16
	s_addc_u32 s17, s13, s17
	global_load_dword v61, v15, s[16:17]
	s_lshl_b64 s[16:17], s[10:11], 12
	v_lshl_add_u64 v[62:63], v[4:5], 0, s[16:17]
	s_add_i32 s0, s0, s1
	s_ashr_i32 s10, s0, 3
	s_add_i32 s10, s10, s22
	s_ashr_i32 s11, s10, 31
	s_lshl_b64 s[16:17], s[10:11], 5
	s_add_u32 s16, s2, s16
	s_addc_u32 s17, s3, s17
	s_add_u32 s16, s16, s14
	s_addc_u32 s17, s17, 0
	global_load_dword v64, v1, s[16:17]
	s_add_u32 s16, s16, 0x40000
	s_addc_u32 s17, s17, 0
	global_load_dword v65, v1, s[16:17]
	s_add_u32 s16, s16, 0x40000
	s_addc_u32 s17, s17, 0
	global_load_dword v66, v1, s[16:17]
	s_lshl_b64 s[16:17], s[10:11], 11
	s_add_u32 s16, s4, s16
	s_addc_u32 s17, s5, s17
	global_load_dword v67, v15, s[16:17]
	s_lshl_b64 s[16:17], s[10:11], 11
	s_add_u32 s16, s6, s16
	s_addc_u32 s17, s7, s17
	global_load_dword v68, v15, s[16:17]
	s_lshl_b64 s[16:17], s[10:11], 11
	s_add_u32 s16, s12, s16
	s_addc_u32 s17, s13, s17
	global_load_dword v69, v15, s[16:17]
	s_lshl_b64 s[16:17], s[10:11], 12
	v_lshl_add_u64 v[70:71], v[4:5], 0, s[16:17]
	s_add_i32 s0, s0, s1
	s_ashr_i32 s10, s0, 3
	s_add_i32 s10, s10, s22
	s_ashr_i32 s11, s10, 31
	s_lshl_b64 s[16:17], s[10:11], 5
	s_add_u32 s16, s2, s16
	s_addc_u32 s17, s3, s17
	s_add_u32 s16, s16, s14
	s_addc_u32 s17, s17, 0
	global_load_dword v72, v1, s[16:17]
	s_add_u32 s16, s16, 0x40000
	s_addc_u32 s17, s17, 0
	global_load_dword v73, v1, s[16:17]
	s_add_u32 s16, s16, 0x40000
	s_addc_u32 s17, s17, 0
	global_load_dword v74, v1, s[16:17]
	s_lshl_b64 s[16:17], s[10:11], 11
	s_add_u32 s16, s4, s16
	s_addc_u32 s17, s5, s17
	global_load_dword v75, v15, s[16:17]
	s_lshl_b64 s[16:17], s[10:11], 11
	s_add_u32 s16, s6, s16
	s_addc_u32 s17, s7, s17
	global_load_dword v76, v15, s[16:17]
	s_lshl_b64 s[16:17], s[10:11], 11
	s_add_u32 s16, s12, s16
	s_addc_u32 s17, s13, s17
	global_load_dword v77, v15, s[16:17]
	s_lshl_b64 s[16:17], s[10:11], 12
	v_lshl_add_u64 v[78:79], v[4:5], 0, s[16:17]
	s_add_i32 s0, s0, s1
	s_mov_b32 s15, 0xffff0000
	s_waitcnt vmcnt(42)
	v_max3_f32 v9, v16, v17, v18
	v_sub_f32_e32 v0, v16, v9
	v_exp_f32_e32 v6, v0
	v_sub_f32_e32 v0, v17, v9
	v_exp_f32_e32 v7, v0
	v_sub_f32_e32 v0, v18, v9
	v_exp_f32_e32 v8, v0
	v_add_f32_e32 v0, v6, v7
	v_add_f32_e32 v0, v8, v0
	v_div_scale_f32 v9, s[16:17], v0, v0, 1.0
	v_rcp_f32_e32 v10, v9
	s_nop 0
	v_fma_f32 v11, -v9, v10, 1.0
	v_fmac_f32_e32 v10, v11, v10
	v_div_scale_f32 v11, vcc, 1.0, v0, 1.0
	v_mul_f32_e32 v12, v11, v10
	v_fma_f32 v13, -v9, v12, v11
	v_fmac_f32_e32 v12, v13, v10
	v_fma_f32 v9, -v9, v12, v11
	v_div_fmas_f32 v9, v9, v10, v12
	v_div_fixup_f32 v0, v9, v0, 1.0
	v_pk_mul_f32 v[6:7], v[6:7], v[0:1] op_sel_hi:[1,0]
	v_mul_f32_e32 v8, v8, v0
	v_cvt_f32_f16_sdwa v11, v19 dst_sel:DWORD dst_unused:UNUSED_PAD src0_sel:WORD_1
	v_cvt_f32_f16_e32 v12, v19
	v_cvt_f32_f16_e32 v10, v20
	v_cvt_f32_f16_sdwa v13, v20 dst_sel:DWORD dst_unused:UNUSED_PAD src0_sel:WORD_1
	v_pk_mul_f32 v[10:11], v[6:7], v[10:11] op_sel:[1,0] op_sel_hi:[0,1]
	v_pk_fma_f32 v[6:7], v[6:7], v[12:13], v[10:11]
	v_cvt_f32_f16_e32 v10, v21
	v_cvt_f32_f16_sdwa v11, v21 dst_sel:DWORD dst_unused:UNUSED_PAD src0_sel:WORD_1
	v_pk_fma_f32 v[6:7], v[8:9], v[10:11], v[6:7] op_sel_hi:[0,1,1]
	v_and_b32_sdwa v8, v6, v201 dst_sel:DWORD dst_unused:UNUSED_PAD src0_sel:WORD_1 src1_sel:DWORD
	v_and_b32_sdwa v0, v7, v201 dst_sel:DWORD dst_unused:UNUSED_PAD src0_sel:WORD_1 src1_sel:DWORD
	v_add3_u32 v6, v6, v8, s71
	v_add3_u32 v0, v7, v0, s71
	v_lshrrev_b32_e32 v6, 16, v6
	v_and_or_b32 v0, v0, s15, v6
	global_store_dword v[22:23], v0, off
	s_waitcnt vmcnt(37)
	v_max3_f32 v9, v24, v25, v26
	v_sub_f32_e32 v0, v24, v9
	v_exp_f32_e32 v6, v0
	v_sub_f32_e32 v0, v25, v9
	v_exp_f32_e32 v7, v0
	v_sub_f32_e32 v0, v26, v9
	v_exp_f32_e32 v8, v0
	v_add_f32_e32 v0, v6, v7
	v_add_f32_e32 v0, v8, v0
	v_div_scale_f32 v9, s[16:17], v0, v0, 1.0
	v_rcp_f32_e32 v10, v9
	s_nop 0
	v_fma_f32 v11, -v9, v10, 1.0
	v_fmac_f32_e32 v10, v11, v10
	v_div_scale_f32 v11, vcc, 1.0, v0, 1.0
	v_mul_f32_e32 v12, v11, v10
	v_fma_f32 v13, -v9, v12, v11
	v_fmac_f32_e32 v12, v13, v10
	v_fma_f32 v9, -v9, v12, v11
	v_div_fmas_f32 v9, v9, v10, v12
	v_div_fixup_f32 v0, v9, v0, 1.0
	v_pk_mul_f32 v[6:7], v[6:7], v[0:1] op_sel_hi:[1,0]
	v_mul_f32_e32 v8, v8, v0
	v_cvt_f32_f16_sdwa v11, v27 dst_sel:DWORD dst_unused:UNUSED_PAD src0_sel:WORD_1
	v_cvt_f32_f16_e32 v12, v27
	v_cvt_f32_f16_e32 v10, v28
	v_cvt_f32_f16_sdwa v13, v28 dst_sel:DWORD dst_unused:UNUSED_PAD src0_sel:WORD_1
	v_pk_mul_f32 v[10:11], v[6:7], v[10:11] op_sel:[1,0] op_sel_hi:[0,1]
	v_pk_fma_f32 v[6:7], v[6:7], v[12:13], v[10:11]
	v_cvt_f32_f16_e32 v10, v29
	v_cvt_f32_f16_sdwa v11, v29 dst_sel:DWORD dst_unused:UNUSED_PAD src0_sel:WORD_1
	v_pk_fma_f32 v[6:7], v[8:9], v[10:11], v[6:7] op_sel_hi:[0,1,1]
	v_and_b32_sdwa v8, v6, v201 dst_sel:DWORD dst_unused:UNUSED_PAD src0_sel:WORD_1 src1_sel:DWORD
	v_and_b32_sdwa v0, v7, v201 dst_sel:DWORD dst_unused:UNUSED_PAD src0_sel:WORD_1 src1_sel:DWORD
	v_add3_u32 v6, v6, v8, s71
	v_add3_u32 v0, v7, v0, s71
	v_lshrrev_b32_e32 v6, 16, v6
	v_and_or_b32 v0, v0, s15, v6
	global_store_dword v[30:31], v0, off
	s_waitcnt vmcnt(32)
	v_max3_f32 v9, v32, v33, v34
	v_sub_f32_e32 v0, v32, v9
	v_exp_f32_e32 v6, v0
	v_sub_f32_e32 v0, v33, v9
	v_exp_f32_e32 v7, v0
	v_sub_f32_e32 v0, v34, v9
	v_exp_f32_e32 v8, v0
	v_add_f32_e32 v0, v6, v7
	v_add_f32_e32 v0, v8, v0
	v_div_scale_f32 v9, s[16:17], v0, v0, 1.0
	v_rcp_f32_e32 v10, v9
	s_nop 0
	v_fma_f32 v11, -v9, v10, 1.0
	v_fmac_f32_e32 v10, v11, v10
	v_div_scale_f32 v11, vcc, 1.0, v0, 1.0
	v_mul_f32_e32 v12, v11, v10
	v_fma_f32 v13, -v9, v12, v11
	v_fmac_f32_e32 v12, v13, v10
	v_fma_f32 v9, -v9, v12, v11
	v_div_fmas_f32 v9, v9, v10, v12
	v_div_fixup_f32 v0, v9, v0, 1.0
	v_pk_mul_f32 v[6:7], v[6:7], v[0:1] op_sel_hi:[1,0]
	v_mul_f32_e32 v8, v8, v0
	v_cvt_f32_f16_sdwa v11, v35 dst_sel:DWORD dst_unused:UNUSED_PAD src0_sel:WORD_1
	v_cvt_f32_f16_e32 v12, v35
	v_cvt_f32_f16_e32 v10, v36
	v_cvt_f32_f16_sdwa v13, v36 dst_sel:DWORD dst_unused:UNUSED_PAD src0_sel:WORD_1
	v_pk_mul_f32 v[10:11], v[6:7], v[10:11] op_sel:[1,0] op_sel_hi:[0,1]
	v_pk_fma_f32 v[6:7], v[6:7], v[12:13], v[10:11]
	v_cvt_f32_f16_e32 v10, v37
	v_cvt_f32_f16_sdwa v11, v37 dst_sel:DWORD dst_unused:UNUSED_PAD src0_sel:WORD_1
	v_pk_fma_f32 v[6:7], v[8:9], v[10:11], v[6:7] op_sel_hi:[0,1,1]
	v_and_b32_sdwa v8, v6, v201 dst_sel:DWORD dst_unused:UNUSED_PAD src0_sel:WORD_1 src1_sel:DWORD
	v_and_b32_sdwa v0, v7, v201 dst_sel:DWORD dst_unused:UNUSED_PAD src0_sel:WORD_1 src1_sel:DWORD
	v_add3_u32 v6, v6, v8, s71
	v_add3_u32 v0, v7, v0, s71
	v_lshrrev_b32_e32 v6, 16, v6
	v_and_or_b32 v0, v0, s15, v6
	global_store_dword v[38:39], v0, off
	s_waitcnt vmcnt(27)
	v_max3_f32 v9, v40, v41, v42
	v_sub_f32_e32 v0, v40, v9
	v_exp_f32_e32 v6, v0
	v_sub_f32_e32 v0, v41, v9
	v_exp_f32_e32 v7, v0
	v_sub_f32_e32 v0, v42, v9
	v_exp_f32_e32 v8, v0
	v_add_f32_e32 v0, v6, v7
	v_add_f32_e32 v0, v8, v0
	v_div_scale_f32 v9, s[16:17], v0, v0, 1.0
	v_rcp_f32_e32 v10, v9
	s_nop 0
	v_fma_f32 v11, -v9, v10, 1.0
	v_fmac_f32_e32 v10, v11, v10
	v_div_scale_f32 v11, vcc, 1.0, v0, 1.0
	v_mul_f32_e32 v12, v11, v10
	v_fma_f32 v13, -v9, v12, v11
	v_fmac_f32_e32 v12, v13, v10
	v_fma_f32 v9, -v9, v12, v11
	v_div_fmas_f32 v9, v9, v10, v12
	v_div_fixup_f32 v0, v9, v0, 1.0
	v_pk_mul_f32 v[6:7], v[6:7], v[0:1] op_sel_hi:[1,0]
	v_mul_f32_e32 v8, v8, v0
	v_cvt_f32_f16_sdwa v11, v43 dst_sel:DWORD dst_unused:UNUSED_PAD src0_sel:WORD_1
	v_cvt_f32_f16_e32 v12, v43
	v_cvt_f32_f16_e32 v10, v44
	v_cvt_f32_f16_sdwa v13, v44 dst_sel:DWORD dst_unused:UNUSED_PAD src0_sel:WORD_1
	v_pk_mul_f32 v[10:11], v[6:7], v[10:11] op_sel:[1,0] op_sel_hi:[0,1]
	v_pk_fma_f32 v[6:7], v[6:7], v[12:13], v[10:11]
	v_cvt_f32_f16_e32 v10, v45
	v_cvt_f32_f16_sdwa v11, v45 dst_sel:DWORD dst_unused:UNUSED_PAD src0_sel:WORD_1
	v_pk_fma_f32 v[6:7], v[8:9], v[10:11], v[6:7] op_sel_hi:[0,1,1]
	v_and_b32_sdwa v8, v6, v201 dst_sel:DWORD dst_unused:UNUSED_PAD src0_sel:WORD_1 src1_sel:DWORD
	v_and_b32_sdwa v0, v7, v201 dst_sel:DWORD dst_unused:UNUSED_PAD src0_sel:WORD_1 src1_sel:DWORD
	v_add3_u32 v6, v6, v8, s71
	v_add3_u32 v0, v7, v0, s71
	v_lshrrev_b32_e32 v6, 16, v6
	v_and_or_b32 v0, v0, s15, v6
	global_store_dword v[46:47], v0, off
	s_waitcnt vmcnt(22)
	v_max3_f32 v9, v48, v49, v50
	v_sub_f32_e32 v0, v48, v9
	v_exp_f32_e32 v6, v0
	v_sub_f32_e32 v0, v49, v9
	v_exp_f32_e32 v7, v0
	v_sub_f32_e32 v0, v50, v9
	v_exp_f32_e32 v8, v0
	v_add_f32_e32 v0, v6, v7
	v_add_f32_e32 v0, v8, v0
	v_div_scale_f32 v9, s[16:17], v0, v0, 1.0
	v_rcp_f32_e32 v10, v9
	s_nop 0
	v_fma_f32 v11, -v9, v10, 1.0
	v_fmac_f32_e32 v10, v11, v10
	v_div_scale_f32 v11, vcc, 1.0, v0, 1.0
	v_mul_f32_e32 v12, v11, v10
	v_fma_f32 v13, -v9, v12, v11
	v_fmac_f32_e32 v12, v13, v10
	v_fma_f32 v9, -v9, v12, v11
	v_div_fmas_f32 v9, v9, v10, v12
	v_div_fixup_f32 v0, v9, v0, 1.0
	v_pk_mul_f32 v[6:7], v[6:7], v[0:1] op_sel_hi:[1,0]
	v_mul_f32_e32 v8, v8, v0
	v_cvt_f32_f16_sdwa v11, v51 dst_sel:DWORD dst_unused:UNUSED_PAD src0_sel:WORD_1
	v_cvt_f32_f16_e32 v12, v51
	v_cvt_f32_f16_e32 v10, v52
	v_cvt_f32_f16_sdwa v13, v52 dst_sel:DWORD dst_unused:UNUSED_PAD src0_sel:WORD_1
	v_pk_mul_f32 v[10:11], v[6:7], v[10:11] op_sel:[1,0] op_sel_hi:[0,1]
	v_pk_fma_f32 v[6:7], v[6:7], v[12:13], v[10:11]
	v_cvt_f32_f16_e32 v10, v53
	v_cvt_f32_f16_sdwa v11, v53 dst_sel:DWORD dst_unused:UNUSED_PAD src0_sel:WORD_1
	v_pk_fma_f32 v[6:7], v[8:9], v[10:11], v[6:7] op_sel_hi:[0,1,1]
	v_and_b32_sdwa v8, v6, v201 dst_sel:DWORD dst_unused:UNUSED_PAD src0_sel:WORD_1 src1_sel:DWORD
	v_and_b32_sdwa v0, v7, v201 dst_sel:DWORD dst_unused:UNUSED_PAD src0_sel:WORD_1 src1_sel:DWORD
	v_add3_u32 v6, v6, v8, s71
	v_add3_u32 v0, v7, v0, s71
	v_lshrrev_b32_e32 v6, 16, v6
	v_and_or_b32 v0, v0, s15, v6
	global_store_dword v[54:55], v0, off
	s_waitcnt vmcnt(17)
	v_max3_f32 v9, v56, v57, v58
	v_sub_f32_e32 v0, v56, v9
	v_exp_f32_e32 v6, v0
	v_sub_f32_e32 v0, v57, v9
	v_exp_f32_e32 v7, v0
	v_sub_f32_e32 v0, v58, v9
	v_exp_f32_e32 v8, v0
	v_add_f32_e32 v0, v6, v7
	v_add_f32_e32 v0, v8, v0
	v_div_scale_f32 v9, s[16:17], v0, v0, 1.0
	v_rcp_f32_e32 v10, v9
	s_nop 0
	v_fma_f32 v11, -v9, v10, 1.0
	v_fmac_f32_e32 v10, v11, v10
	v_div_scale_f32 v11, vcc, 1.0, v0, 1.0
	v_mul_f32_e32 v12, v11, v10
	v_fma_f32 v13, -v9, v12, v11
	v_fmac_f32_e32 v12, v13, v10
	v_fma_f32 v9, -v9, v12, v11
	v_div_fmas_f32 v9, v9, v10, v12
	v_div_fixup_f32 v0, v9, v0, 1.0
	v_pk_mul_f32 v[6:7], v[6:7], v[0:1] op_sel_hi:[1,0]
	v_mul_f32_e32 v8, v8, v0
	v_cvt_f32_f16_sdwa v11, v59 dst_sel:DWORD dst_unused:UNUSED_PAD src0_sel:WORD_1
	v_cvt_f32_f16_e32 v12, v59
	v_cvt_f32_f16_e32 v10, v60
	v_cvt_f32_f16_sdwa v13, v60 dst_sel:DWORD dst_unused:UNUSED_PAD src0_sel:WORD_1
	v_pk_mul_f32 v[10:11], v[6:7], v[10:11] op_sel:[1,0] op_sel_hi:[0,1]
	v_pk_fma_f32 v[6:7], v[6:7], v[12:13], v[10:11]
	v_cvt_f32_f16_e32 v10, v61
	v_cvt_f32_f16_sdwa v11, v61 dst_sel:DWORD dst_unused:UNUSED_PAD src0_sel:WORD_1
	v_pk_fma_f32 v[6:7], v[8:9], v[10:11], v[6:7] op_sel_hi:[0,1,1]
	v_and_b32_sdwa v8, v6, v201 dst_sel:DWORD dst_unused:UNUSED_PAD src0_sel:WORD_1 src1_sel:DWORD
	v_and_b32_sdwa v0, v7, v201 dst_sel:DWORD dst_unused:UNUSED_PAD src0_sel:WORD_1 src1_sel:DWORD
	v_add3_u32 v6, v6, v8, s71
	v_add3_u32 v0, v7, v0, s71
	v_lshrrev_b32_e32 v6, 16, v6
	v_and_or_b32 v0, v0, s15, v6
	global_store_dword v[62:63], v0, off
	s_waitcnt vmcnt(12)
	v_max3_f32 v9, v64, v65, v66
	v_sub_f32_e32 v0, v64, v9
	v_exp_f32_e32 v6, v0
	v_sub_f32_e32 v0, v65, v9
	v_exp_f32_e32 v7, v0
	v_sub_f32_e32 v0, v66, v9
	v_exp_f32_e32 v8, v0
	v_add_f32_e32 v0, v6, v7
	v_add_f32_e32 v0, v8, v0
	v_div_scale_f32 v9, s[16:17], v0, v0, 1.0
	v_rcp_f32_e32 v10, v9
	s_nop 0
	v_fma_f32 v11, -v9, v10, 1.0
	v_fmac_f32_e32 v10, v11, v10
	v_div_scale_f32 v11, vcc, 1.0, v0, 1.0
	v_mul_f32_e32 v12, v11, v10
	v_fma_f32 v13, -v9, v12, v11
	v_fmac_f32_e32 v12, v13, v10
	v_fma_f32 v9, -v9, v12, v11
	v_div_fmas_f32 v9, v9, v10, v12
	v_div_fixup_f32 v0, v9, v0, 1.0
	v_pk_mul_f32 v[6:7], v[6:7], v[0:1] op_sel_hi:[1,0]
	v_mul_f32_e32 v8, v8, v0
	v_cvt_f32_f16_sdwa v11, v67 dst_sel:DWORD dst_unused:UNUSED_PAD src0_sel:WORD_1
	v_cvt_f32_f16_e32 v12, v67
	v_cvt_f32_f16_e32 v10, v68
	v_cvt_f32_f16_sdwa v13, v68 dst_sel:DWORD dst_unused:UNUSED_PAD src0_sel:WORD_1
	v_pk_mul_f32 v[10:11], v[6:7], v[10:11] op_sel:[1,0] op_sel_hi:[0,1]
	v_pk_fma_f32 v[6:7], v[6:7], v[12:13], v[10:11]
	v_cvt_f32_f16_e32 v10, v69
	v_cvt_f32_f16_sdwa v11, v69 dst_sel:DWORD dst_unused:UNUSED_PAD src0_sel:WORD_1
	v_pk_fma_f32 v[6:7], v[8:9], v[10:11], v[6:7] op_sel_hi:[0,1,1]
	v_and_b32_sdwa v8, v6, v201 dst_sel:DWORD dst_unused:UNUSED_PAD src0_sel:WORD_1 src1_sel:DWORD
	v_and_b32_sdwa v0, v7, v201 dst_sel:DWORD dst_unused:UNUSED_PAD src0_sel:WORD_1 src1_sel:DWORD
	v_add3_u32 v6, v6, v8, s71
	v_add3_u32 v0, v7, v0, s71
	v_lshrrev_b32_e32 v6, 16, v6
	v_and_or_b32 v0, v0, s15, v6
	global_store_dword v[70:71], v0, off
	s_waitcnt vmcnt(7)
	v_max3_f32 v9, v72, v73, v74
	v_sub_f32_e32 v0, v72, v9
	v_exp_f32_e32 v6, v0
	v_sub_f32_e32 v0, v73, v9
	v_exp_f32_e32 v7, v0
	v_sub_f32_e32 v0, v74, v9
	v_exp_f32_e32 v8, v0
	v_add_f32_e32 v0, v6, v7
	v_add_f32_e32 v0, v8, v0
	v_div_scale_f32 v9, s[16:17], v0, v0, 1.0
	v_rcp_f32_e32 v10, v9
	s_nop 0
	v_fma_f32 v11, -v9, v10, 1.0
	v_fmac_f32_e32 v10, v11, v10
	v_div_scale_f32 v11, vcc, 1.0, v0, 1.0
	v_mul_f32_e32 v12, v11, v10
	v_fma_f32 v13, -v9, v12, v11
	v_fmac_f32_e32 v12, v13, v10
	v_fma_f32 v9, -v9, v12, v11
	v_div_fmas_f32 v9, v9, v10, v12
	v_div_fixup_f32 v0, v9, v0, 1.0
	v_pk_mul_f32 v[6:7], v[6:7], v[0:1] op_sel_hi:[1,0]
	v_mul_f32_e32 v8, v8, v0
	v_cvt_f32_f16_sdwa v11, v75 dst_sel:DWORD dst_unused:UNUSED_PAD src0_sel:WORD_1
	v_cvt_f32_f16_e32 v12, v75
	v_cvt_f32_f16_e32 v10, v76
	v_cvt_f32_f16_sdwa v13, v76 dst_sel:DWORD dst_unused:UNUSED_PAD src0_sel:WORD_1
	v_pk_mul_f32 v[10:11], v[6:7], v[10:11] op_sel:[1,0] op_sel_hi:[0,1]
	v_pk_fma_f32 v[6:7], v[6:7], v[12:13], v[10:11]
	v_cvt_f32_f16_e32 v10, v77
	v_cvt_f32_f16_sdwa v11, v77 dst_sel:DWORD dst_unused:UNUSED_PAD src0_sel:WORD_1
	v_pk_fma_f32 v[6:7], v[8:9], v[10:11], v[6:7] op_sel_hi:[0,1,1]
	v_and_b32_sdwa v8, v6, v201 dst_sel:DWORD dst_unused:UNUSED_PAD src0_sel:WORD_1 src1_sel:DWORD
	v_and_b32_sdwa v0, v7, v201 dst_sel:DWORD dst_unused:UNUSED_PAD src0_sel:WORD_1 src1_sel:DWORD
	v_add3_u32 v6, v6, v8, s71
	v_add3_u32 v0, v7, v0, s71
	v_lshrrev_b32_e32 v6, 16, v6
	v_and_or_b32 v0, v0, s15, v6
	global_store_dword v[78:79], v0, off
	s_cmp_lt_i32 s0, 0x8000
	s_cbranch_scc1 .Lcmb_blk
	s_branch .LBB0_331
